# XCD-local seams: wait on the arrival counter reaching its target (one memory hop) instead of the leader's release word (two hops); release word compared monotonically everywhere
# baseline (speedup 1.0000x reference)
.Lxb0_276:
	s_or_b64 exec, exec, s[10:11]
	v_cvt_f32_u32_e32 v4, v2
	s_waitcnt vmcnt(0)
	v_readfirstlane_b32 s0, v3
	v_sub_u32_e32 v3, 0, v2
	v_rcp_iflag_f32_e32 v4, v4
	v_add_u32_e32 v5, s0, v1
	v_mul_f32_e32 v4, 0x4f7ffffe, v4
	v_cvt_u32_f32_e32 v4, v4
	v_mul_lo_u32 v1, v3, v4
	v_mul_hi_u32 v1, v4, v1
	v_add_u32_e32 v1, v4, v1
	v_mul_hi_u32 v1, v5, v1
	v_mul_lo_u32 v3, v1, v2
	v_sub_u32_e32 v3, v5, v3
	v_add_u32_e32 v4, 1, v1
	v_cmp_ge_u32_e32 vcc, v3, v2
	s_nop 1
	v_cndmask_b32_e32 v1, v1, v4, vcc
	v_sub_u32_e32 v4, v3, v2
	v_cndmask_b32_e32 v3, v3, v4, vcc
	v_add_u32_e32 v4, 1, v1
	v_cmp_ge_u32_e32 vcc, v3, v2
	v_add_u32_e32 v3, 1, v5
	s_nop 0
	v_cndmask_b32_e32 v1, v1, v4, vcc
	v_mul_lo_u32 v4, v2, v1
	v_add_u32_e32 v2, v4, v2
	v_cmp_ne_u32_e32 vcc, v3, v2
	s_and_saveexec_b64 s[0:1], vcc
	s_xor_b64 s[8:9], exec, s[0:1]
	s_cbranch_execz .Lxb0_290
	s_waitcnt lgkmcnt(0)
	v_mov_b32_e32 v0, 0x2000
	global_load_dword v0, v0, s[6:7] offset:1024 sc1
	s_add_u32 s12, s6, 0x2400
	s_addc_u32 s13, s7, 0
	s_waitcnt vmcnt(0)
	v_cmp_le_u32_e32 vcc, v0, v1
	s_and_saveexec_b64 s[10:11], vcc
	s_cbranch_execz .Lxb0_289
	s_mov_b32 s0, 1
	s_mov_b64 s[14:15], 0
	v_mov_b32_e32 v0, 0
	s_branch .Lxb0_280

.Lxb0_282:
	global_load_dword v2, v0, s[12:13] sc1
	s_add_i32 s0, s0, 1
	s_mov_b64 s[20:21], -1
	s_waitcnt vmcnt(0)
	v_cmp_gt_u32_e32 vcc, v2, v1
	s_orn2_b64 s[18:19], vcc, exec
	s_branch .Lxb0_279

.LBB0_276:
	s_or_b64 exec, exec, s[10:11]
	v_cvt_f32_u32_e32 v4, v2
	s_waitcnt vmcnt(0)
	v_readfirstlane_b32 s0, v3
	v_sub_u32_e32 v3, 0, v2
	v_rcp_iflag_f32_e32 v4, v4
	v_add_u32_e32 v5, s0, v1
	v_mul_f32_e32 v4, 0x4f7ffffe, v4
	v_cvt_u32_f32_e32 v4, v4
	v_mul_lo_u32 v1, v3, v4
	v_mul_hi_u32 v1, v4, v1
	v_add_u32_e32 v1, v4, v1
	v_mul_hi_u32 v1, v5, v1
	v_mul_lo_u32 v3, v1, v2
	v_sub_u32_e32 v3, v5, v3
	v_add_u32_e32 v4, 1, v1
	v_cmp_ge_u32_e32 vcc, v3, v2
	s_nop 1
	v_cndmask_b32_e32 v1, v1, v4, vcc
	v_sub_u32_e32 v4, v3, v2
	v_cndmask_b32_e32 v3, v3, v4, vcc
	v_add_u32_e32 v4, 1, v1
	v_cmp_ge_u32_e32 vcc, v3, v2
	v_add_u32_e32 v3, 1, v5
	s_nop 0
	v_cndmask_b32_e32 v1, v1, v4, vcc
	v_mul_lo_u32 v4, v2, v1
	v_add_u32_e32 v2, v4, v2
	v_cmp_ne_u32_e32 vcc, v3, v2
	s_and_saveexec_b64 s[0:1], vcc
	s_xor_b64 s[8:9], exec, s[0:1]
	s_cbranch_execz .LBB0_290
	s_waitcnt lgkmcnt(0)
	v_mov_b32_e32 v1, v2
	v_mov_b32_e32 v0, 0x1000
	global_load_dword v0, v0, s[6:7] offset:1024 sc1
	s_add_u32 s12, s6, 0x1400
	s_addc_u32 s13, s7, 0
	s_waitcnt vmcnt(0)
	v_cmp_lt_u32_e32 vcc, v0, v1
	s_and_saveexec_b64 s[10:11], vcc
	s_cbranch_execz .LBB0_289
	s_mov_b32 s0, 1
	s_mov_b64 s[14:15], 0
	v_mov_b32_e32 v0, 0
	s_branch .LBB0_280

.LBB0_282:
	global_load_dword v2, v0, s[12:13] sc1
	s_add_i32 s0, s0, 1
	s_mov_b64 s[20:21], -1
	s_waitcnt vmcnt(0)
	v_cmp_ge_u32_e32 vcc, v2, v1
	s_orn2_b64 s[18:19], vcc, exec
	s_branch .LBB0_279

.LBB0_832:
	s_or_b64 exec, exec, s[12:13]
	v_cvt_f32_u32_e32 v4, v2
	s_waitcnt vmcnt(0)
	v_readfirstlane_b32 s0, v3
	v_sub_u32_e32 v3, 0, v2
	v_rcp_iflag_f32_e32 v4, v4
	v_add_u32_e32 v5, s0, v1
	v_mul_f32_e32 v4, 0x4f7ffffe, v4
	v_cvt_u32_f32_e32 v4, v4
	v_mul_lo_u32 v1, v3, v4
	v_mul_hi_u32 v1, v4, v1
	v_add_u32_e32 v1, v4, v1
	v_mul_hi_u32 v1, v5, v1
	v_mul_lo_u32 v3, v1, v2
	v_sub_u32_e32 v3, v5, v3
	v_add_u32_e32 v4, 1, v1
	v_cmp_ge_u32_e32 vcc, v3, v2
	s_nop 1
	v_cndmask_b32_e32 v1, v1, v4, vcc
	v_sub_u32_e32 v4, v3, v2
	v_cndmask_b32_e32 v3, v3, v4, vcc
	v_add_u32_e32 v4, 1, v1
	v_cmp_ge_u32_e32 vcc, v3, v2
	v_add_u32_e32 v3, 1, v5
	s_nop 0
	v_cndmask_b32_e32 v1, v1, v4, vcc
	v_mul_lo_u32 v4, v2, v1
	v_add_u32_e32 v2, v4, v2
	v_cmp_ne_u32_e32 vcc, v3, v2
	s_and_saveexec_b64 s[0:1], vcc
	s_xor_b64 s[10:11], exec, s[0:1]
	s_cbranch_execz .LBB0_846
	s_waitcnt lgkmcnt(0)
	v_mov_b32_e32 v0, 0x2000
	global_load_dword v0, v0, s[6:7] offset:1024 sc1
	s_add_u32 s14, s6, 0x2400
	s_addc_u32 s15, s7, 0
	s_waitcnt vmcnt(0)
	v_cmp_le_u32_e32 vcc, v0, v1
	s_and_saveexec_b64 s[12:13], vcc
	s_cbranch_execz .LBB0_845
	s_mov_b32 s0, 1
	s_mov_b64 s[16:17], 0
	v_mov_b32_e32 v0, 0
	s_branch .LBB0_836

.LBB0_838:
	global_load_dword v2, v0, s[14:15] sc1
	s_add_i32 s0, s0, 1
	s_mov_b64 s[22:23], -1
	s_waitcnt vmcnt(0)
	v_cmp_gt_u32_e32 vcc, v2, v1
	s_orn2_b64 s[20:21], vcc, exec
	s_branch .LBB0_835

.LBB0_963:
	s_or_b64 exec, exec, s[12:13]
	v_cvt_f32_u32_e32 v4, v2
	s_waitcnt vmcnt(0)
	v_readfirstlane_b32 s2, v3
	v_sub_u32_e32 v3, 0, v2
	v_rcp_iflag_f32_e32 v4, v4
	v_add_u32_e32 v5, s2, v1
	v_mul_f32_e32 v4, 0x4f7ffffe, v4
	v_cvt_u32_f32_e32 v4, v4
	v_mul_lo_u32 v1, v3, v4
	v_mul_hi_u32 v1, v4, v1
	v_add_u32_e32 v1, v4, v1
	v_mul_hi_u32 v1, v5, v1
	v_mul_lo_u32 v3, v1, v2
	v_sub_u32_e32 v3, v5, v3
	v_add_u32_e32 v4, 1, v1
	v_cmp_ge_u32_e32 vcc, v3, v2
	s_nop 1
	v_cndmask_b32_e32 v1, v1, v4, vcc
	v_sub_u32_e32 v4, v3, v2
	v_cndmask_b32_e32 v3, v3, v4, vcc
	v_add_u32_e32 v4, 1, v1
	v_cmp_ge_u32_e32 vcc, v3, v2
	v_add_u32_e32 v3, 1, v5
	s_nop 0
	v_cndmask_b32_e32 v1, v1, v4, vcc
	v_mul_lo_u32 v4, v2, v1
	v_add_u32_e32 v2, v4, v2
	v_cmp_ne_u32_e32 vcc, v3, v2
	s_and_saveexec_b64 s[2:3], vcc
	s_xor_b64 s[10:11], exec, s[2:3]
	s_cbranch_execz .LBB0_977
	s_waitcnt lgkmcnt(0)
	v_mov_b32_e32 v0, 0x2000
	global_load_dword v0, v0, s[6:7] offset:1024 sc1
	s_add_u32 s14, s6, 0x2400
	s_addc_u32 s15, s7, 0
	s_waitcnt vmcnt(0)
	v_cmp_le_u32_e32 vcc, v0, v1
	s_and_saveexec_b64 s[12:13], vcc
	s_cbranch_execz .LBB0_976
	s_mov_b32 s2, 1
	s_mov_b64 s[16:17], 0
	v_mov_b32_e32 v0, 0
	s_branch .LBB0_967

.LBB0_969:
	global_load_dword v2, v0, s[14:15] sc1
	s_add_i32 s2, s2, 1
	s_mov_b64 s[22:23], -1
	s_waitcnt vmcnt(0)
	v_cmp_gt_u32_e32 vcc, v2, v1
	s_orn2_b64 s[20:21], vcc, exec
	s_branch .LBB0_966

.LBB0_3425:
	s_or_b64 exec, exec, s[6:7]
	v_cvt_f32_u32_e32 v4, v2
	s_waitcnt vmcnt(0)
	v_readfirstlane_b32 s4, v3
	v_sub_u32_e32 v3, 0, v2
	v_rcp_iflag_f32_e32 v4, v4
	v_add_u32_e32 v5, s4, v1
	v_mul_f32_e32 v4, 0x4f7ffffe, v4
	v_cvt_u32_f32_e32 v4, v4
	v_mul_lo_u32 v1, v3, v4
	v_mul_hi_u32 v1, v4, v1
	v_add_u32_e32 v1, v4, v1
	v_mul_hi_u32 v1, v5, v1
	v_mul_lo_u32 v3, v1, v2
	v_sub_u32_e32 v3, v5, v3
	v_add_u32_e32 v4, 1, v1
	v_cmp_ge_u32_e32 vcc, v3, v2
	s_nop 1
	v_cndmask_b32_e32 v1, v1, v4, vcc
	v_sub_u32_e32 v4, v3, v2
	v_cndmask_b32_e32 v3, v3, v4, vcc
	v_add_u32_e32 v4, 1, v1
	v_cmp_ge_u32_e32 vcc, v3, v2
	v_add_u32_e32 v3, 1, v5
	s_nop 0
	v_cndmask_b32_e32 v1, v1, v4, vcc
	v_mul_lo_u32 v4, v2, v1
	v_add_u32_e32 v2, v4, v2
	v_cmp_ne_u32_e32 vcc, v3, v2
	s_and_saveexec_b64 s[4:5], vcc
	s_xor_b64 s[4:5], exec, s[4:5]
	s_cbranch_execz .LBB0_3439
	s_waitcnt lgkmcnt(0)
	v_mov_b32_e32 v0, 0x2000
	global_load_dword v0, v0, s[2:3] offset:1024 sc1
	s_add_u32 s8, s2, 0x2400
	s_addc_u32 s9, s3, 0
	s_waitcnt vmcnt(0)
	v_cmp_le_u32_e32 vcc, v0, v1
	s_and_saveexec_b64 s[6:7], vcc
	s_cbranch_execz .LBB0_3438
	s_mov_b32 s20, 1
	s_mov_b64 s[10:11], 0
	v_mov_b32_e32 v0, 0
	s_branch .LBB0_3429

.LBB0_3431:
	global_load_dword v2, v0, s[8:9] sc1
	s_add_i32 s20, s20, 1
	s_mov_b64 s[16:17], -1
	s_waitcnt vmcnt(0)
	v_cmp_gt_u32_e32 vcc, v2, v1
	s_orn2_b64 s[14:15], vcc, exec
	s_branch .LBB0_3428
